# mlC: transposed V LDS tile XOR-swizzled (even chunk XOR) so the 2-byte transposing stores are at most 2-way bank conflicted (was 8-way)
# speedup vs baseline: 1.0043x; 1.0027x over previous
.LBB0_1202:
	s_add_u32 s18, s88, 0x1b000000
	s_addc_u32 s19, s89, 0
	s_and_b64 vcc, exec, s[42:43]
	s_cbranch_vccnz .LBB0_1298
	v_cmp_eq_u32_e64 s[2:3], 0, v1
	v_ashrrev_i32_e32 v81, 31, v80
	v_lshl_add_u64 v[4:5], v[80:81], 4, s[88:89]
	v_writelane_b32 v255, s2, 38
	v_lshlrev_b32_e32 v112, 5, v1
	v_and_b32_e32 v3, 31, v80
	v_writelane_b32 v255, s3, 39
	s_mov_b64 s[2:3], 0x1db00000
	v_lshl_add_u64 v[82:83], v[4:5], 0, s[2:3]
	v_lshl_add_u64 v[4:5], s[88:89], 0, v[112:113]
	s_add_u32 s2, s88, 0x1fe28000
	v_lshl_add_u64 v[84:85], v[4:5], 0, s[94:95]
	v_writelane_b32 v255, s2, 40
	s_addc_u32 s2, s89, 0
	v_lshrrev_b32_e32 v4, 1, v80
	v_writelane_b32 v255, s2, 41
	s_add_u32 s2, s88, 0x1fe30000
	v_and_b32_e32 v5, 32, v4
	v_ashrrev_i32_e32 v4, 2, v80
	v_writelane_b32 v255, s2, 42
	v_and_b32_e32 v86, 0xffffffe0, v4
	v_bfi_b32 v4, s92, v4, v80
	v_lshrrev_b32_e32 v6, 5, v0
	v_writelane_b32 v255, s88, 43
	v_mul_lo_u32 v4, v4, s20
	s_addc_u32 s2, s89, 0
	v_writelane_b32 v255, s89, 44
	v_or_b32_e32 v11, v5, v3
	v_add_u32_e32 v105, 0, v4
	v_lshlrev_b32_e32 v4, 2, v6
	v_lshlrev_b32_e32 v7, 2, v0
	v_writelane_b32 v255, s2, 45
	v_cmp_le_u32_e64 s[2:3], v4, v11
	v_add_u32_e32 v97, 0, v7
	v_xor_b32_e32 v98, 4, v7
	v_xor_b32_e32 v99, 8, v7
	v_xor_b32_e32 v100, 16, v7
	v_xor_b32_e32 v106, 0x80, v7
	v_or_b32_e32 v7, 32, v4
	v_writelane_b32 v255, s2, 46
	v_or_b32_e32 v14, 34, v4
	v_cmp_le_u32_e64 s[56:57], v14, v11
	v_writelane_b32 v255, s3, 47
	v_cmp_le_u32_e64 s[2:3], v7, v11
	v_or_b32_e32 v7, 33, v4
	v_cmp_le_u32_e64 s[52:53], v7, v11
	v_or_b32_e32 v7, 2, v4
	v_cmp_le_u32_e64 s[54:55], v7, v11
	v_or_b32_e32 v7, 3, v4
	v_or_b32_e32 v14, 35, v4
	v_cmp_le_u32_e64 s[58:59], v7, v11
	v_cmp_le_u32_e64 s[60:61], v14, v11
	v_or_b32_e32 v7, 8, v4
	v_or_b32_e32 v14, 40, v4
	v_cmp_le_u32_e64 s[62:63], v7, v11
	v_cmp_le_u32_e64 s[64:65], v14, v11
	v_or_b32_e32 v7, 9, v4
	v_or_b32_e32 v14, 41, v4
	v_cmp_le_u32_e64 s[66:67], v7, v11
	v_cmp_le_u32_e64 s[68:69], v14, v11
	v_or_b32_e32 v7, 10, v4
	v_or_b32_e32 v14, 42, v4
	v_cmp_le_u32_e64 s[70:71], v7, v11
	v_cmp_le_u32_e64 s[72:73], v14, v11
	v_or_b32_e32 v7, 11, v4
	v_or_b32_e32 v14, 43, v4
	v_cmp_le_u32_e64 s[44:45], v7, v11
	v_cmp_le_u32_e64 s[46:47], v14, v11
	v_or_b32_e32 v7, 16, v4
	v_or_b32_e32 v14, 48, v4
	v_cmp_le_u32_e64 s[78:79], v7, v11
	v_cmp_le_u32_e64 s[80:81], v14, v11
	v_or_b32_e32 v7, 17, v4
	v_or_b32_e32 v14, 49, v4
	s_mov_b64 s[16:17], s[82:83]
	v_cmp_le_u32_e64 s[82:83], v7, v11
	v_cmp_le_u32_e64 s[84:85], v14, v11
	v_or_b32_e32 v7, 18, v4
	v_or_b32_e32 v14, 50, v4
	v_mul_lo_u32 v2, v94, s20
	v_writelane_b32 v255, s2, 48
	v_cmp_le_u32_e64 s[50:51], v7, v11
	v_cmp_le_u32_e64 s[88:89], v14, v11
	v_or_b32_e32 v7, 19, v4
	v_or_b32_e32 v14, 51, v4
	v_add_u32_e32 v8, 0, v2
	v_lshlrev_b32_e32 v9, 4, v1
	v_lshlrev_b32_e32 v2, 3, v1
	v_bitop3_b32 v109, v5, s90, v3 bitop3:0x36
	v_mad_u32_u24 v1, v1, s91, 0
	v_writelane_b32 v255, s3, 49
	v_cmp_lt_u32_e64 s[2:3], v4, v11
	v_cmp_le_u32_e64 s[90:91], v7, v11
	v_cmp_le_u32_e64 s[92:93], v14, v11
	v_or_b32_e32 v7, 24, v4
	v_or_b32_e32 v14, 56, v4
	v_readlane_b32 s6, v254, 35
	v_writelane_b32 v255, s2, 50
	v_cmp_le_u32_e64 s[94:95], v7, v11
	v_cmp_le_u32_e64 s[96:97], v14, v11
	v_or_b32_e32 v7, 25, v4
	v_or_b32_e32 v14, 57, v4
	v_lshl_add_u32 v101, v94, 2, s6
	v_lshl_add_u32 v107, v11, 2, s6
	v_writelane_b32 v255, s3, 51
	v_cmp_le_u32_e64 s[40:41], v7, v11
	v_cmp_le_u32_e64 s[6:7], v14, v11
	v_or_b32_e32 v7, 26, v4
	v_or_b32_e32 v14, 58, v4
	v_readlane_b32 s3, v254, 27
	s_lshl_b32 s77, s86, 6
	s_movk_i32 s2, 0x10ff
	v_lshlrev_b32_e32 v10, 1, v94
	v_mad_u32_u24 v103, v11, s20, 0
	v_lshlrev_b32_e32 v104, 4, v6
	v_mad_u32_u24 v12, v3, s20, 0
	v_mul_i32_i24_e32 v13, 0xffffff74, v11
	v_lshlrev_b32_e32 v6, 3, v6
	v_cmp_le_u32_e64 s[8:9], v7, v11
	v_cmp_le_u32_e64 s[10:11], v14, v11
	v_or_b32_e32 v7, 27, v4
	v_or_b32_e32 v14, 59, v4
	v_add3_u32 v111, s3, v5, v3
	s_waitcnt vmcnt(0)
	v_bitop3_b32 v114, v5, s2, v3 bitop3:0x36
	v_add_u32_e32 v3, s77, v94
	v_cmp_gt_u32_e64 s[42:43], 64, v80
	v_add_u32_e32 v102, 0xffffff00, v94
	v_mov_b32_e32 v81, v113
	v_or_b32_e32 v108, 0xffffff00, v11
	v_ashrrev_i32_e32 v87, 31, v86
	v_add_u32_e32 v110, 0, v104
	v_cmp_le_u32_e64 s[12:13], v7, v11
	v_cmp_le_u32_e64 s[14:15], v14, v11
	v_sub_u32_e32 v115, 0, v3
	v_add_u32_e32 v116, v8, v9
	v_add_u32_e32 v117, v1, v10
	v_lshlrev_b32_e32 v88, 1, v2
	v_lshlrev_b32_e32 v90, 2, v0
	v_add_u32_e32 v118, v12, v104
	v_add_u32_e32 v119, v105, v6
	v_lshrrev_b32_e32 v134, 3, v80
	v_and_b32_e32 v135, 7, v80
	v_and_b32_e32 v136, 3, v135
	v_lshlrev_b32_e32 v136, 1, v136
	v_lshrrev_b32_e32 v137, 3, v134
	v_xor_b32_e32 v137, v137, v136
	v_and_b32_e32 v138, 7, v134
	v_lshlrev_b32_e32 v138, 1, v138
	v_lshl_add_u32 v138, v137, 4, v138
	v_mul_u32_u24_e32 v139, 0x480, v135
	v_add_u32_e32 v117, v139, v138
	v_and_b32_e32 v140, 31, v80
	v_lshrrev_b32_e32 v141, 7, v80
	v_lshl_or_b32 v140, v141, 5, v140
	v_bfe_u32 v140, v140, 3, 2
	v_lshlrev_b32_e32 v140, 1, v140
	v_xor_b32_e32 v141, 0, v140
	v_lshlrev_b32_e32 v141, 4, v141
	v_add_u32_e32 v141, 0x6800, v141
	v_add_u32_e32 v142, v141, v119
	v_xor_b32_e32 v141, 2, v140
	v_lshlrev_b32_e32 v141, 4, v141
	v_add_u32_e32 v141, 0x6800, v141
	v_add_u32_e32 v143, v141, v119
	v_xor_b32_e32 v141, 4, v140
	v_lshlrev_b32_e32 v141, 4, v141
	v_add_u32_e32 v141, 0x6800, v141
	v_add_u32_e32 v144, v141, v119
	v_xor_b32_e32 v141, 6, v140
	v_lshlrev_b32_e32 v141, 4, v141
	v_add_u32_e32 v141, 0x6800, v141
	v_add_u32_e32 v145, v141, v119
	v_lshlrev_b32_e32 v112, 1, v4
	v_add_u32_e32 v120, v103, v13
	v_readlane_b32 s48, v254, 28
	s_mov_b32 s49, s16
	s_branch .LBB0_1205

.LBB0_1287:
	s_or_b64 exec, exec, s[16:17]
	v_add_f32_e32 v31, v122, v32
	v_add_f32_e32 v31, 0, v31
	v_add_f32_e32 v47, v121, v16
	v_add_f32_e32 v31, v31, v47
	v_add_f32_e32 v47, v33, v17
	v_add_f32_e32 v31, v31, v47
	v_add_f32_e32 v47, v34, v18
	v_add_f32_e32 v31, v31, v47
	v_add_f32_e32 v47, v35, v19
	v_add_f32_e32 v31, v31, v47
	v_add_f32_e32 v47, v36, v20
	v_add_f32_e32 v31, v31, v47
	v_add_f32_e32 v47, v37, v21
	v_add_f32_e32 v31, v31, v47
	v_add_f32_e32 v47, v38, v22
	v_add_f32_e32 v31, v31, v47
	v_add_f32_e32 v47, v39, v23
	v_add_f32_e32 v31, v31, v47
	v_add_f32_e32 v47, v40, v24
	v_add_f32_e32 v31, v31, v47
	v_add_f32_e32 v47, v41, v25
	v_add_f32_e32 v31, v31, v47
	v_add_f32_e32 v47, v42, v26
	v_add_f32_e32 v31, v31, v47
	v_add_f32_e32 v47, v43, v27
	v_add_f32_e32 v31, v31, v47
	v_add_f32_e32 v47, v44, v28
	v_add_f32_e32 v31, v31, v47
	v_add_f32_e32 v47, v45, v29
	v_add_f32_e32 v31, v31, v47
	v_add_u32_e32 v47, 0x6800, v119
	ds_read2_b64 v[124:127], v142 offset0:128 offset1:130
	v_mul_f32_e32 v0, v0, v93
	v_mul_f32_e32 v1, v1, v93
	v_mul_f32_e32 v2, v2, v93
	v_mul_f32_e32 v3, v3, v93
	v_mul_f32_e32 v4, v4, v93
	v_mul_f32_e32 v5, v5, v93
	v_mul_f32_e32 v6, v6, v93
	v_mul_f32_e32 v7, v7, v93
	v_mul_f32_e32 v8, v8, v93
	v_mul_f32_e32 v9, v9, v93
	v_mul_f32_e32 v10, v10, v93
	v_mul_f32_e32 v11, v11, v93
	v_mul_f32_e32 v12, v12, v93
	v_mul_f32_e32 v13, v13, v93
	v_mul_f32_e32 v14, v14, v93
	v_mul_f32_e32 v15, v15, v93
	v_cvt_pk_bf16_f32 v128, v122, v121
	v_cvt_pk_bf16_f32 v129, v33, v34
	v_cvt_pk_bf16_f32 v130, v35, v36
	v_cvt_pk_bf16_f32 v131, v37, v38
	ds_read2_b64 v[34:37], v143 offset0:128 offset1:130
	v_cvt_pk_bf16_f32 v38, v39, v40
	s_waitcnt lgkmcnt(0)
	v_mfma_f32_32x32x16_bf16 v[0:15], v[124:127], v[128:131], v[0:15]
	v_cvt_pk_bf16_f32 v39, v41, v42
	v_cvt_pk_bf16_f32 v40, v43, v44
	v_cvt_pk_bf16_f32 v41, v45, v46
	ds_read2_b64 v[42:45], v144 offset0:128 offset1:130
	v_add_f32_e32 v33, v46, v30
	v_add_f32_e32 v31, v31, v33
	v_cvt_pk_bf16_f32 v16, v32, v16
	v_mfma_f32_32x32x16_bf16 v[0:15], v[34:37], v[38:41], v[0:15]
	v_cvt_pk_bf16_f32 v17, v17, v18
	v_cvt_pk_bf16_f32 v18, v19, v20
	v_cvt_pk_bf16_f32 v19, v21, v22
	ds_read2_b64 v[32:35], v145 offset0:128 offset1:130
	v_cvt_pk_bf16_f32 v20, v23, v24
	v_cvt_pk_bf16_f32 v21, v25, v26
	v_cvt_pk_bf16_f32 v22, v27, v28
	s_waitcnt lgkmcnt(0)
	v_mfma_f32_32x32x16_bf16 v[0:15], v[42:45], v[16:19], v[0:15]
	v_cvt_pk_bf16_f32 v23, v29, v30
	s_mul_hi_i32 s3, s49, 0x78787879
	s_lshr_b32 s16, s3, 31
	s_ashr_i32 s3, s3, 5
	s_add_i32 s3, s3, s16
	s_mul_i32 s16, s3, 0xffffffbc
	ds_bpermute_b32 v17, v106, v31
	v_mfma_f32_32x32x16_bf16 v[0:15], v[32:35], v[20:23], v[0:15]
	ds_read_b32 v18, v107
	ds_read_b32 v19, v120 offset:65024
	s_add_i32 s38, s49, s16
	s_and_b32 s39, s3, 1
	s_ashr_i32 s34, s3, 3
	s_cmp_eq_u32 s39, 0
	s_cselect_b64 s[16:17], -1, 0
	s_cmp_eq_u32 s39, 1
	s_cselect_b64 vcc, -1, 0
	s_cmp_gt_i32 s38, 3
	s_mov_b64 s[38:39], -1
	s_cbranch_scc0 .LBB0_1293
	s_andn2_b64 vcc, exec, vcc
	s_cbranch_vccnz .LBB0_1290
	s_mul_i32 s38, s3, 0x1100
	s_add_i32 s38, s38, s48
	v_add_u32_e32 v16, s38, v114
	s_mov_b64 s[38:39], 0
